# fused epilogues: arrive at the unit barrier once the partial-sum stores are out (counted wait), early loads stay in flight
# baseline (speedup 1.0000x reference)
;     __device__ __forceinline__ void operator()(const pg8::f32x4 (&acc)[2][2][4][2], const pg8::Unit& u, int wr, int wc, int fr, int fq) const {
;     ...
;             for (int m = 0; m < 4; ++m) {
;                 const int row = row0 + ai * 128 + m * 16;
;                 const size_t off = (size_t)row * D + col0;
;                 float s = 0.f;
; #pragma unroll
;                 for (int bj = 0; bj < 2; ++bj) {
;                     float r[8];
; #pragma unroll
;                     for (int j = 0; j < 4; ++j) { r[j] = acc[ai][bj][m][0][j]; r[4 + j] = acc[ai][bj][m][1][j]; }
;                     if (RSCALE) { const float rv = rvs[ai][m];
; #pragma unroll
;                         for (int j = 0; j < 8; ++j) r[j] *= rv; }
;                     if (ACT == 1) {
; #pragma unroll
;                         for (int j = 0; j < 8; ++j) r[j] = sigmoid_fast(r[j]);
;                     }
;                     if (GATE) { const v4u g = gq[m][bj];
;                         r[0] *= bf_lo(g.x); r[1] *= bf_hi(g.x); r[2] *= bf_lo(g.y); r[3] *= bf_hi(g.y); r[4] *= bf_lo(g.z); r[5] *= bf_hi(g.z); r[6] *= bf_lo(g.w); r[7] *= bf_hi(g.w); }
;                     if (ADD) { const v4u g = aq[m][bj];
;                         r[0] += bf_lo(g.x); r[1] += bf_hi(g.x); r[2] += bf_lo(g.y); r[3] += bf_hi(g.y); r[4] += bf_lo(g.z); r[5] += bf_hi(g.z); r[6] += bf_lo(g.w); r[7] += bf_hi(g.w); }
;                     if (PART) {
; #pragma unroll
;                         for (int j = 0; j < 8; ++j) s += r[j] * r[j];
;                     }
;                     v4u w; w.x = pk2(r[0], r[1]); w.y = pk2(r[2], r[3]); w.z = pk2(r[4], r[5]); w.w = pk2(r[6], r[7]);
;                     st16_wt(O + off + bj * 128, w);
;                 }
;                 if (PART) { s += __shfl_xor(s, 16); s += __shfl_xor(s, 32); st4_wt(part + (size_t)row * 16 + u.pn * 4 + wc, s); }
; template <bool SRC_F32, int R> __device__ __forceinline__ void ew_load(EwSet<SRC_F32, R>& S, int rb, const float* hsrc32, const bf16* hsrcb, const bf16* f, const float* part, int lane) {
; #pragma unroll
;     for (int i = 0; i < R; ++i) S.p[i] = (lane < 16) ? part[(size_t)(rb + i) * 16 + lane] : 0.f;
; #pragma unroll
;     for (int i = 0; i < R; ++i)
; #pragma unroll
;         for (int j = 0; j < 4; ++j) {
;             S.fw[i][j] = ((const v2u*)(f + (size_t)(rb + i) * D) + lane)[64 * j];
.LBB0_332:
	s_waitcnt lgkmcnt(0)
	v_lshl_or_b32 v242, s62, 8, v148
	v_lshl_add_u32 v243, s61, 8, v146
	v_lshlrev_b32_e32 v246, 2, v242
	v_lshlrev_b32_e32 v153, 1, v242
	v_lshl_add_u32 v153, v243, 11, v153
	v_xor_b32_e32 v166, 16, v152
	v_lshlrev_b32_e32 v166, 2, v166
	v_xor_b32_e32 v168, 32, v152
	v_lshlrev_b32_e32 v168, 2, v168
	v_lshrrev_b32_e32 v161, 4, v152
	v_and_b32_e32 v161, 3, v161
	v_lshlrev_b32_e32 v161, 4, v161
	v_lshl_add_u32 v161, v243, 6, v161
	s_lshl_b32 s95, s62, 4
	s_add_u32 s95, s95, s14
	v_lshl_add_u32 v157, v243, 6, s95
	v_pk_mul_f32 v[242:243], v[124:125], v[124:125]
	v_pk_fma_f32 v[242:243], v[126:127], v[126:127], v[242:243]
	v_pk_fma_f32 v[242:243], v[120:121], v[120:121], v[242:243]
	v_pk_fma_f32 v[242:243], v[122:123], v[122:123], v[242:243]
	v_pk_fma_f32 v[242:243], v[116:117], v[116:117], v[242:243]
	v_pk_fma_f32 v[242:243], v[118:119], v[118:119], v[242:243]
	v_pk_fma_f32 v[242:243], v[112:113], v[112:113], v[242:243]
	v_pk_fma_f32 v[242:243], v[114:115], v[114:115], v[242:243]
	v_add_f32_e32 v145, v242, v243
	v_pk_mul_f32 v[244:245], v[108:109], v[108:109]
	v_pk_fma_f32 v[244:245], v[110:111], v[110:111], v[244:245]
	v_pk_fma_f32 v[244:245], v[104:105], v[104:105], v[244:245]
	v_pk_fma_f32 v[244:245], v[106:107], v[106:107], v[244:245]
	v_pk_fma_f32 v[244:245], v[100:101], v[100:101], v[244:245]
	v_pk_fma_f32 v[244:245], v[102:103], v[102:103], v[244:245]
	v_pk_fma_f32 v[244:245], v[96:97], v[96:97], v[244:245]
	v_pk_fma_f32 v[244:245], v[98:99], v[98:99], v[244:245]
	v_add_f32_e32 v155, v244, v245
	v_pk_mul_f32 v[242:243], v[92:93], v[92:93]
	v_pk_fma_f32 v[242:243], v[94:95], v[94:95], v[242:243]
	v_pk_fma_f32 v[242:243], v[88:89], v[88:89], v[242:243]
	v_pk_fma_f32 v[242:243], v[90:91], v[90:91], v[242:243]
	v_pk_fma_f32 v[242:243], v[84:85], v[84:85], v[242:243]
	v_pk_fma_f32 v[242:243], v[86:87], v[86:87], v[242:243]
	v_pk_fma_f32 v[242:243], v[80:81], v[80:81], v[242:243]
	v_pk_fma_f32 v[242:243], v[82:83], v[82:83], v[242:243]
	v_add_f32_e32 v159, v242, v243
	v_pk_mul_f32 v[244:245], v[76:77], v[76:77]
	v_pk_fma_f32 v[244:245], v[78:79], v[78:79], v[244:245]
	v_pk_fma_f32 v[244:245], v[72:73], v[72:73], v[244:245]
	v_pk_fma_f32 v[244:245], v[74:75], v[74:75], v[244:245]
	v_pk_fma_f32 v[244:245], v[68:69], v[68:69], v[244:245]
	v_pk_fma_f32 v[244:245], v[70:71], v[70:71], v[244:245]
	v_pk_fma_f32 v[244:245], v[64:65], v[64:65], v[244:245]
	v_pk_fma_f32 v[244:245], v[66:67], v[66:67], v[244:245]
	v_add_f32_e32 v163, v244, v245
	v_pk_mul_f32 v[242:243], v[60:61], v[60:61]
	v_pk_fma_f32 v[242:243], v[62:63], v[62:63], v[242:243]
	v_pk_fma_f32 v[242:243], v[56:57], v[56:57], v[242:243]
	v_pk_fma_f32 v[242:243], v[58:59], v[58:59], v[242:243]
	v_pk_fma_f32 v[242:243], v[52:53], v[52:53], v[242:243]
	v_pk_fma_f32 v[242:243], v[54:55], v[54:55], v[242:243]
	v_pk_fma_f32 v[242:243], v[48:49], v[48:49], v[242:243]
	v_pk_fma_f32 v[242:243], v[50:51], v[50:51], v[242:243]
	v_add_f32_e32 v165, v242, v243
	v_pk_mul_f32 v[244:245], v[44:45], v[44:45]
	v_pk_fma_f32 v[244:245], v[46:47], v[46:47], v[244:245]
	v_pk_fma_f32 v[244:245], v[40:41], v[40:41], v[244:245]
	v_pk_fma_f32 v[244:245], v[42:43], v[42:43], v[244:245]
	v_pk_fma_f32 v[244:245], v[36:37], v[36:37], v[244:245]
	v_pk_fma_f32 v[244:245], v[38:39], v[38:39], v[244:245]
	v_pk_fma_f32 v[244:245], v[32:33], v[32:33], v[244:245]
	v_pk_fma_f32 v[244:245], v[34:35], v[34:35], v[244:245]
	v_add_f32_e32 v171, v244, v245
	v_pk_mul_f32 v[242:243], v[28:29], v[28:29]
	v_pk_fma_f32 v[242:243], v[30:31], v[30:31], v[242:243]
	v_pk_fma_f32 v[242:243], v[24:25], v[24:25], v[242:243]
	v_pk_fma_f32 v[242:243], v[26:27], v[26:27], v[242:243]
	v_pk_fma_f32 v[242:243], v[20:21], v[20:21], v[242:243]
	v_pk_fma_f32 v[242:243], v[22:23], v[22:23], v[242:243]
	v_pk_fma_f32 v[242:243], v[16:17], v[16:17], v[242:243]
	v_pk_fma_f32 v[242:243], v[18:19], v[18:19], v[242:243]
	v_add_f32_e32 v193, v242, v243
	v_pk_mul_f32 v[244:245], v[12:13], v[12:13]
	v_pk_fma_f32 v[244:245], v[14:15], v[14:15], v[244:245]
	v_pk_fma_f32 v[244:245], v[8:9], v[8:9], v[244:245]
	v_pk_fma_f32 v[244:245], v[10:11], v[10:11], v[244:245]
	v_pk_fma_f32 v[244:245], v[4:5], v[4:5], v[244:245]
	v_pk_fma_f32 v[244:245], v[6:7], v[6:7], v[244:245]
	v_pk_fma_f32 v[244:245], v[0:1], v[0:1], v[244:245]
	v_pk_fma_f32 v[244:245], v[2:3], v[2:3], v[244:245]
	v_add_f32_e32 v241, v244, v245
	s_nop 1
	ds_bpermute_b32 v188, v166, v145
	ds_bpermute_b32 v196, v166, v155
	ds_bpermute_b32 v200, v166, v159
	ds_bpermute_b32 v204, v166, v163
	ds_bpermute_b32 v208, v166, v165
	ds_bpermute_b32 v212, v166, v171
	ds_bpermute_b32 v216, v166, v193
	ds_bpermute_b32 v220, v166, v241
	s_waitcnt lgkmcnt(0)
	v_add_f32_e32 v145, v145, v188
	v_add_f32_e32 v155, v155, v196
	v_add_f32_e32 v159, v159, v200
	v_add_f32_e32 v163, v163, v204
	v_add_f32_e32 v165, v165, v208
	v_add_f32_e32 v171, v171, v212
	v_add_f32_e32 v193, v193, v216
	v_add_f32_e32 v241, v241, v220
	s_nop 1
	ds_bpermute_b32 v188, v168, v145
	ds_bpermute_b32 v196, v168, v155
	ds_bpermute_b32 v200, v168, v159
	ds_bpermute_b32 v204, v168, v163
	ds_bpermute_b32 v208, v168, v165
	ds_bpermute_b32 v212, v168, v171
	ds_bpermute_b32 v216, v168, v193
	ds_bpermute_b32 v220, v168, v241
	s_waitcnt lgkmcnt(0)
	v_add_f32_e32 v145, v145, v188
	v_add_f32_e32 v155, v155, v196
	v_add_f32_e32 v159, v159, v200
	v_add_f32_e32 v163, v163, v204
	v_add_f32_e32 v165, v165, v208
	v_add_f32_e32 v171, v171, v212
	v_add_f32_e32 v193, v193, v216
	v_add_f32_e32 v241, v241, v220
	global_store_dword v157, v145, s[20:21]
	v_add_u32_e32 v196, 0x400, v157
	global_store_dword v196, v155, s[20:21]
	v_add_u32_e32 v200, 0x800, v157
	global_store_dword v200, v159, s[20:21]
	v_add_u32_e32 v204, 0xc00, v157
	global_store_dword v204, v163, s[20:21]
	v_add_u32_e32 v208, 0x2000, v157
	global_store_dword v208, v165, s[20:21]
	v_add_u32_e32 v212, 0x2400, v157
	global_store_dword v212, v171, s[20:21]
	v_add_u32_e32 v216, 0x2800, v157
	global_store_dword v216, v193, s[20:21]
	v_add_u32_e32 v220, 0x2c00, v157
	global_store_dword v220, v241, s[20:21]
	s_add_u32 s62, s84, 0xffffff10
	s_addc_u32 s63, s85, -1
	s_load_dwordx2 s[64:65], s[62:63], 0x30
	s_add_u32 s66, s28, 0x5000000
	s_addc_u32 s67, s29, 0
	s_add_u32 s78, s28, 0x4c00000
	s_addc_u32 s79, s29, 0
	global_load_dwordx4 v[224:227], v153, s[66:67]
	global_load_dwordx4 v[228:231], v153, s[66:67] offset:256
	v_add_u32_e32 v244, 0x8000, v153
	global_load_dwordx4 v[232:235], v244, s[66:67]
	global_load_dwordx4 v[236:239], v244, s[66:67] offset:256
	s_waitcnt lgkmcnt(0)
	global_load_dwordx4 v[172:175], v246, s[64:65]
	global_load_dwordx4 v[176:179], v246, s[64:65] offset:16
	global_load_dwordx4 v[180:183], v246, s[64:65] offset:512
	global_load_dwordx4 v[184:187], v246, s[64:65] offset:528
	s_waitcnt vmcnt(8)
	s_barrier
; __device__ __forceinline__ unsigned xb_add(unsigned* p, unsigned v) { return __hip_atomic_fetch_add(p, v, __ATOMIC_RELAXED, __HIP_MEMORY_SCOPE_AGENT); }
; __device__ __forceinline__ void xcd_barrier(const XcdBarrier& b) {
;     ...
;     if (threadIdx.x == 0) {
;         unsigned* bar = b.bar;
;         __builtin_amdgcn_s_waitcnt(0);
;         unsigned nloc = b.st[0], nx = b.st[1];
;         if (nloc == 0u) { xcd_barrier_complete(bar, b.x, nloc, nx); b.st[0] = nloc; b.st[1] = nx; }
;         const unsigned old = xb_add(&bar[XB_XSUB(b.x)], 1u);
;         const unsigned gen = old / nloc;
;         if (old + 1u == (gen + 1u) * nloc) {
;             __builtin_amdgcn_fence(__ATOMIC_RELEASE, "agent");
;             asm volatile("s_waitcnt vmcnt(0)" ::: "memory");
;             const unsigned og = xb_add(&bar[XB_TOP], 1u);
	v_readfirstlane_b32 s94, v195
	s_cmp_lg_u32 s94, 0
	s_cbranch_scc1 .Lfe0_bskip
	s_mov_b64 exec, 1
	s_and_b32 s94, s2, 7
	s_lshl_b32 s94, s94, 3
	s_bfe_u32 s96, s2, 0x30003
	s_or_b32 s94, s94, s96
	s_lshl_b32 s94, s94, 5
	s_add_u32 s62, s28, 0x3903600
	s_addc_u32 s63, s29, 0
	v_mov_b32_e32 v242, s94
	v_mov_b32_e32 v243, 1
	s_cmp_eq_u32 s99, 1
	s_cbranch_scc1 .Lfe0_bfast
	buffer_wbl2 sc1
	s_waitcnt vmcnt(0)

;     __device__ __forceinline__ void operator()(const pg8::f32x4 (&acc)[2][2][4][2], const pg8::Unit& u, int wr, int wc, int fr, int fq) const {
;     ...
;             for (int m = 0; m < 4; ++m) {
;                 const int row = row0 + ai * 128 + m * 16;
;                 const size_t off = (size_t)row * D + col0;
;                 float s = 0.f;
; #pragma unroll
;                 for (int bj = 0; bj < 2; ++bj) {
;                     float r[8];
; #pragma unroll
;                     for (int j = 0; j < 4; ++j) { r[j] = acc[ai][bj][m][0][j]; r[4 + j] = acc[ai][bj][m][1][j]; }
;                     if (RSCALE) { const float rv = rvs[ai][m];
; #pragma unroll
;                         for (int j = 0; j < 8; ++j) r[j] *= rv; }
;                     if (ACT == 1) {
; #pragma unroll
;                         for (int j = 0; j < 8; ++j) r[j] = sigmoid_fast(r[j]);
;                     }
;                     if (GATE) { const v4u g = gq[m][bj];
;                         r[0] *= bf_lo(g.x); r[1] *= bf_hi(g.x); r[2] *= bf_lo(g.y); r[3] *= bf_hi(g.y); r[4] *= bf_lo(g.z); r[5] *= bf_hi(g.z); r[6] *= bf_lo(g.w); r[7] *= bf_hi(g.w); }
;                     if (ADD) { const v4u g = aq[m][bj];
;                         r[0] += bf_lo(g.x); r[1] += bf_hi(g.x); r[2] += bf_lo(g.y); r[3] += bf_hi(g.y); r[4] += bf_lo(g.z); r[5] += bf_hi(g.z); r[6] += bf_lo(g.w); r[7] += bf_hi(g.w); }
;                     if (PART) {
; #pragma unroll
;                         for (int j = 0; j < 8; ++j) s += r[j] * r[j];
;                     }
;                     v4u w; w.x = pk2(r[0], r[1]); w.y = pk2(r[2], r[3]); w.z = pk2(r[4], r[5]); w.w = pk2(r[6], r[7]);
;                     st16_wt(O + off + bj * 128, w);
;                 }
;                 if (PART) { s += __shfl_xor(s, 16); s += __shfl_xor(s, 32); st4_wt(part + (size_t)row * 16 + u.pn * 4 + wc, s); }
; template <bool SRC_F32, int R> __device__ __forceinline__ void ew_load(EwSet<SRC_F32, R>& S, int rb, const float* hsrc32, const bf16* hsrcb, const bf16* f, const float* part, int lane) {
; #pragma unroll
;     for (int i = 0; i < R; ++i) S.p[i] = (lane < 16) ? part[(size_t)(rb + i) * 16 + lane] : 0.f;
; #pragma unroll
;     for (int i = 0; i < R; ++i)
; #pragma unroll
;         for (int j = 0; j < 4; ++j) {
;             S.fw[i][j] = ((const v2u*)(f + (size_t)(rb + i) * D) + lane)[64 * j];
.LBB0_889:
	s_waitcnt lgkmcnt(0)
	v_lshl_or_b32 v242, s41, 8, v148
	v_lshl_add_u32 v243, s40, 8, v146
	v_lshlrev_b32_e32 v194, 2, v242
	v_lshlrev_b32_e32 v153, 1, v242
	v_lshl_add_u32 v153, v243, 11, v153
	v_xor_b32_e32 v166, 16, v152
	v_lshlrev_b32_e32 v166, 2, v166
	v_xor_b32_e32 v168, 32, v152
	v_lshlrev_b32_e32 v168, 2, v168
	v_lshrrev_b32_e32 v161, 4, v152
	v_and_b32_e32 v161, 3, v161
	v_lshlrev_b32_e32 v161, 4, v161
	v_lshl_add_u32 v161, v243, 6, v161
	s_lshl_b32 s95, s41, 4
	s_add_u32 s95, s95, s6
	v_lshl_add_u32 v157, v243, 6, s95
	v_pk_mul_f32 v[242:243], v[124:125], v[124:125]
	v_pk_fma_f32 v[242:243], v[126:127], v[126:127], v[242:243]
	v_pk_fma_f32 v[242:243], v[120:121], v[120:121], v[242:243]
	v_pk_fma_f32 v[242:243], v[122:123], v[122:123], v[242:243]
	v_pk_fma_f32 v[242:243], v[116:117], v[116:117], v[242:243]
	v_pk_fma_f32 v[242:243], v[118:119], v[118:119], v[242:243]
	v_pk_fma_f32 v[242:243], v[112:113], v[112:113], v[242:243]
	v_pk_fma_f32 v[242:243], v[114:115], v[114:115], v[242:243]
	v_add_f32_e32 v145, v242, v243
	v_pk_mul_f32 v[244:245], v[108:109], v[108:109]
	v_pk_fma_f32 v[244:245], v[110:111], v[110:111], v[244:245]
	v_pk_fma_f32 v[244:245], v[104:105], v[104:105], v[244:245]
	v_pk_fma_f32 v[244:245], v[106:107], v[106:107], v[244:245]
	v_pk_fma_f32 v[244:245], v[100:101], v[100:101], v[244:245]
	v_pk_fma_f32 v[244:245], v[102:103], v[102:103], v[244:245]
	v_pk_fma_f32 v[244:245], v[96:97], v[96:97], v[244:245]
	v_pk_fma_f32 v[244:245], v[98:99], v[98:99], v[244:245]
	v_add_f32_e32 v155, v244, v245
	v_pk_mul_f32 v[242:243], v[92:93], v[92:93]
	v_pk_fma_f32 v[242:243], v[94:95], v[94:95], v[242:243]
	v_pk_fma_f32 v[242:243], v[88:89], v[88:89], v[242:243]
	v_pk_fma_f32 v[242:243], v[90:91], v[90:91], v[242:243]
	v_pk_fma_f32 v[242:243], v[84:85], v[84:85], v[242:243]
	v_pk_fma_f32 v[242:243], v[86:87], v[86:87], v[242:243]
	v_pk_fma_f32 v[242:243], v[80:81], v[80:81], v[242:243]
	v_pk_fma_f32 v[242:243], v[82:83], v[82:83], v[242:243]
	v_add_f32_e32 v159, v242, v243
	v_pk_mul_f32 v[244:245], v[76:77], v[76:77]
	v_pk_fma_f32 v[244:245], v[78:79], v[78:79], v[244:245]
	v_pk_fma_f32 v[244:245], v[72:73], v[72:73], v[244:245]
	v_pk_fma_f32 v[244:245], v[74:75], v[74:75], v[244:245]
	v_pk_fma_f32 v[244:245], v[68:69], v[68:69], v[244:245]
	v_pk_fma_f32 v[244:245], v[70:71], v[70:71], v[244:245]
	v_pk_fma_f32 v[244:245], v[64:65], v[64:65], v[244:245]
	v_pk_fma_f32 v[244:245], v[66:67], v[66:67], v[244:245]
	v_add_f32_e32 v163, v244, v245
	v_pk_mul_f32 v[242:243], v[60:61], v[60:61]
	v_pk_fma_f32 v[242:243], v[62:63], v[62:63], v[242:243]
	v_pk_fma_f32 v[242:243], v[56:57], v[56:57], v[242:243]
	v_pk_fma_f32 v[242:243], v[58:59], v[58:59], v[242:243]
	v_pk_fma_f32 v[242:243], v[52:53], v[52:53], v[242:243]
	v_pk_fma_f32 v[242:243], v[54:55], v[54:55], v[242:243]
	v_pk_fma_f32 v[242:243], v[48:49], v[48:49], v[242:243]
	v_pk_fma_f32 v[242:243], v[50:51], v[50:51], v[242:243]
	v_add_f32_e32 v165, v242, v243
	v_pk_mul_f32 v[244:245], v[44:45], v[44:45]
	v_pk_fma_f32 v[244:245], v[46:47], v[46:47], v[244:245]
	v_pk_fma_f32 v[244:245], v[40:41], v[40:41], v[244:245]
	v_pk_fma_f32 v[244:245], v[42:43], v[42:43], v[244:245]
	v_pk_fma_f32 v[244:245], v[36:37], v[36:37], v[244:245]
	v_pk_fma_f32 v[244:245], v[38:39], v[38:39], v[244:245]
	v_pk_fma_f32 v[244:245], v[32:33], v[32:33], v[244:245]
	v_pk_fma_f32 v[244:245], v[34:35], v[34:35], v[244:245]
	v_add_f32_e32 v171, v244, v245
	v_pk_mul_f32 v[242:243], v[28:29], v[28:29]
	v_pk_fma_f32 v[242:243], v[30:31], v[30:31], v[242:243]
	v_pk_fma_f32 v[242:243], v[24:25], v[24:25], v[242:243]
	v_pk_fma_f32 v[242:243], v[26:27], v[26:27], v[242:243]
	v_pk_fma_f32 v[242:243], v[20:21], v[20:21], v[242:243]
	v_pk_fma_f32 v[242:243], v[22:23], v[22:23], v[242:243]
	v_pk_fma_f32 v[242:243], v[16:17], v[16:17], v[242:243]
	v_pk_fma_f32 v[242:243], v[18:19], v[18:19], v[242:243]
	v_add_f32_e32 v193, v242, v243
	v_pk_mul_f32 v[244:245], v[12:13], v[12:13]
	v_pk_fma_f32 v[244:245], v[14:15], v[14:15], v[244:245]
	v_pk_fma_f32 v[244:245], v[8:9], v[8:9], v[244:245]
	v_pk_fma_f32 v[244:245], v[10:11], v[10:11], v[244:245]
	v_pk_fma_f32 v[244:245], v[4:5], v[4:5], v[244:245]
	v_pk_fma_f32 v[244:245], v[6:7], v[6:7], v[244:245]
	v_pk_fma_f32 v[244:245], v[0:1], v[0:1], v[244:245]
	v_pk_fma_f32 v[244:245], v[2:3], v[2:3], v[244:245]
	v_add_f32_e32 v241, v244, v245
	s_nop 1
	ds_bpermute_b32 v188, v166, v145
	ds_bpermute_b32 v196, v166, v155
	ds_bpermute_b32 v200, v166, v159
	ds_bpermute_b32 v204, v166, v163
	ds_bpermute_b32 v208, v166, v165
	ds_bpermute_b32 v212, v166, v171
	ds_bpermute_b32 v216, v166, v193
	ds_bpermute_b32 v220, v166, v241
	s_waitcnt lgkmcnt(0)
	v_add_f32_e32 v145, v145, v188
	v_add_f32_e32 v155, v155, v196
	v_add_f32_e32 v159, v159, v200
	v_add_f32_e32 v163, v163, v204
	v_add_f32_e32 v165, v165, v208
	v_add_f32_e32 v171, v171, v212
	v_add_f32_e32 v193, v193, v216
	v_add_f32_e32 v241, v241, v220
	s_nop 1
	ds_bpermute_b32 v188, v168, v145
	ds_bpermute_b32 v196, v168, v155
	ds_bpermute_b32 v200, v168, v159
	ds_bpermute_b32 v204, v168, v163
	ds_bpermute_b32 v208, v168, v165
	ds_bpermute_b32 v212, v168, v171
	ds_bpermute_b32 v216, v168, v193
	ds_bpermute_b32 v220, v168, v241
	s_waitcnt lgkmcnt(0)
	v_add_f32_e32 v145, v145, v188
	v_add_f32_e32 v155, v155, v196
	v_add_f32_e32 v159, v159, v200
	v_add_f32_e32 v163, v163, v204
	v_add_f32_e32 v165, v165, v208
	v_add_f32_e32 v171, v171, v212
	v_add_f32_e32 v193, v193, v216
	v_add_f32_e32 v241, v241, v220
	global_store_dword v157, v145, s[20:21]
	v_add_u32_e32 v196, 0x400, v157
	global_store_dword v196, v155, s[20:21]
	v_add_u32_e32 v200, 0x800, v157
	global_store_dword v200, v159, s[20:21]
	v_add_u32_e32 v204, 0xc00, v157
	global_store_dword v204, v163, s[20:21]
	v_add_u32_e32 v208, 0x2000, v157
	global_store_dword v208, v165, s[20:21]
	v_add_u32_e32 v212, 0x2400, v157
	global_store_dword v212, v171, s[20:21]
	v_add_u32_e32 v216, 0x2800, v157
	global_store_dword v216, v193, s[20:21]
	v_add_u32_e32 v220, 0x2c00, v157
	global_store_dword v220, v241, s[20:21]
	s_add_u32 s62, s84, 0xffffff10
	s_addc_u32 s63, s85, -1
	s_load_dwordx2 s[64:65], s[62:63], 0x88
	s_add_u32 s66, s28, 0x5000000
	s_addc_u32 s67, s29, 0
	s_add_u32 s78, s28, 0x4c00000
	s_addc_u32 s79, s29, 0
	global_load_dwordx4 v[224:227], v153, s[66:67]
	global_load_dwordx4 v[228:231], v153, s[66:67] offset:256
	v_add_u32_e32 v244, 0x8000, v153
	global_load_dwordx4 v[232:235], v244, s[66:67]
	global_load_dwordx4 v[236:239], v244, s[66:67] offset:256
	s_waitcnt lgkmcnt(0)
	global_load_dwordx4 v[172:175], v194, s[64:65]
	global_load_dwordx4 v[176:179], v194, s[64:65] offset:16
	global_load_dwordx4 v[180:183], v194, s[64:65] offset:512
	global_load_dwordx4 v[184:187], v194, s[64:65] offset:528
	s_waitcnt vmcnt(8)
	s_barrier
; __device__ __forceinline__ unsigned xb_add(unsigned* p, unsigned v) { return __hip_atomic_fetch_add(p, v, __ATOMIC_RELAXED, __HIP_MEMORY_SCOPE_AGENT); }
; __device__ __forceinline__ void xcd_barrier(const XcdBarrier& b) {
;     ...
;     if (threadIdx.x == 0) {
;         unsigned* bar = b.bar;
;         __builtin_amdgcn_s_waitcnt(0);
;         unsigned nloc = b.st[0], nx = b.st[1];
;         if (nloc == 0u) { xcd_barrier_complete(bar, b.x, nloc, nx); b.st[0] = nloc; b.st[1] = nx; }
;         const unsigned old = xb_add(&bar[XB_XSUB(b.x)], 1u);
;         const unsigned gen = old / nloc;
;         if (old + 1u == (gen + 1u) * nloc) {
;             __builtin_amdgcn_fence(__ATOMIC_RELEASE, "agent");
;             asm volatile("s_waitcnt vmcnt(0)" ::: "memory");
;             const unsigned og = xb_add(&bar[XB_TOP], 1u);
	v_readfirstlane_b32 s94, v195
	s_cmp_lg_u32 s94, 0
	s_cbranch_scc1 .Lfe1_bskip
	s_mov_b64 exec, 1
	s_and_b32 s94, s2, 7
	s_lshl_b32 s94, s94, 3
	s_bfe_u32 s96, s2, 0x30003
	s_or_b32 s94, s94, s96
	s_lshl_b32 s94, s94, 5
	s_add_u32 s62, s28, 0x3903600
	s_addc_u32 s63, s29, 0
	v_mov_b32_e32 v242, s94
	v_mov_b32_e32 v243, 1
	s_cmp_eq_u32 s99, 1
	s_cbranch_scc1 .Lfe1_bfast
	buffer_wbl2 sc1
	s_waitcnt vmcnt(0)

;     __device__ __forceinline__ void operator()(const pg8::f32x4 (&acc)[2][2][4][2], const pg8::Unit& u, int wr, int wc, int fr, int fq) const {
;     ...
;             for (int m = 0; m < 4; ++m) {
;                 const int row = row0 + ai * 128 + m * 16;
;                 const size_t off = (size_t)row * D + col0;
;                 float s = 0.f;
; #pragma unroll
;                 for (int bj = 0; bj < 2; ++bj) {
;                     float r[8];
; #pragma unroll
;                     for (int j = 0; j < 4; ++j) { r[j] = acc[ai][bj][m][0][j]; r[4 + j] = acc[ai][bj][m][1][j]; }
;                     if (RSCALE) { const float rv = rvs[ai][m];
; #pragma unroll
;                         for (int j = 0; j < 8; ++j) r[j] *= rv; }
;                     if (ACT == 1) {
; #pragma unroll
;                         for (int j = 0; j < 8; ++j) r[j] = sigmoid_fast(r[j]);
;                     }
;                     if (GATE) { const v4u g = gq[m][bj];
;                         r[0] *= bf_lo(g.x); r[1] *= bf_hi(g.x); r[2] *= bf_lo(g.y); r[3] *= bf_hi(g.y); r[4] *= bf_lo(g.z); r[5] *= bf_hi(g.z); r[6] *= bf_lo(g.w); r[7] *= bf_hi(g.w); }
;                     if (ADD) { const v4u g = aq[m][bj];
;                         r[0] += bf_lo(g.x); r[1] += bf_hi(g.x); r[2] += bf_lo(g.y); r[3] += bf_hi(g.y); r[4] += bf_lo(g.z); r[5] += bf_hi(g.z); r[6] += bf_lo(g.w); r[7] += bf_hi(g.w); }
;                     if (PART) {
; #pragma unroll
;                         for (int j = 0; j < 8; ++j) s += r[j] * r[j];
;                     }
;                     v4u w; w.x = pk2(r[0], r[1]); w.y = pk2(r[2], r[3]); w.z = pk2(r[4], r[5]); w.w = pk2(r[6], r[7]);
;                     st16_wt(O + off + bj * 128, w);
;                 }
;                 if (PART) { s += __shfl_xor(s, 16); s += __shfl_xor(s, 32); st4_wt(part + (size_t)row * 16 + u.pn * 4 + wc, s); }
; template <bool SRC_F32, int R> __device__ __forceinline__ void ew_load(EwSet<SRC_F32, R>& S, int rb, const float* hsrc32, const bf16* hsrcb, const bf16* f, const float* part, int lane) {
; #pragma unroll
;     for (int i = 0; i < R; ++i) S.p[i] = (lane < 16) ? part[(size_t)(rb + i) * 16 + lane] : 0.f;
; #pragma unroll
;     for (int i = 0; i < R; ++i)
; #pragma unroll
;         for (int j = 0; j < 4; ++j) {
;             S.fw[i][j] = ((const v2u*)(f + (size_t)(rb + i) * D) + lane)[64 * j];
.LBB0_1159:
	s_waitcnt lgkmcnt(0)
	v_lshl_or_b32 v238, s52, 8, v148
	v_lshl_add_u32 v239, s51, 8, v146
	v_lshlrev_b32_e32 v243, 2, v238
	v_lshlrev_b32_e32 v153, 1, v238
	v_lshl_add_u32 v153, v239, 11, v153
	v_xor_b32_e32 v194, 16, v152
	v_lshlrev_b32_e32 v194, 2, v194
	v_xor_b32_e32 v242, 32, v152
	v_lshlrev_b32_e32 v242, 2, v242
	v_lshrrev_b32_e32 v168, 4, v152
	v_and_b32_e32 v168, 3, v168
	v_lshlrev_b32_e32 v168, 4, v168
	v_lshl_add_u32 v168, v239, 6, v168
	s_lshl_b32 s95, s52, 4
	s_add_u32 s95, s95, s8
	v_lshl_add_u32 v166, v239, 6, s95
	v_pk_mul_f32 v[238:239], v[124:125], v[124:125]
	v_pk_fma_f32 v[238:239], v[126:127], v[126:127], v[238:239]
	v_pk_fma_f32 v[238:239], v[120:121], v[120:121], v[238:239]
	v_pk_fma_f32 v[238:239], v[122:123], v[122:123], v[238:239]
	v_pk_fma_f32 v[238:239], v[116:117], v[116:117], v[238:239]
	v_pk_fma_f32 v[238:239], v[118:119], v[118:119], v[238:239]
	v_pk_fma_f32 v[238:239], v[112:113], v[112:113], v[238:239]
	v_pk_fma_f32 v[238:239], v[114:115], v[114:115], v[238:239]
	v_add_f32_e32 v145, v238, v239
	v_pk_mul_f32 v[240:241], v[108:109], v[108:109]
	v_pk_fma_f32 v[240:241], v[110:111], v[110:111], v[240:241]
	v_pk_fma_f32 v[240:241], v[104:105], v[104:105], v[240:241]
	v_pk_fma_f32 v[240:241], v[106:107], v[106:107], v[240:241]
	v_pk_fma_f32 v[240:241], v[100:101], v[100:101], v[240:241]
	v_pk_fma_f32 v[240:241], v[102:103], v[102:103], v[240:241]
	v_pk_fma_f32 v[240:241], v[96:97], v[96:97], v[240:241]
	v_pk_fma_f32 v[240:241], v[98:99], v[98:99], v[240:241]
	v_add_f32_e32 v155, v240, v241
	v_pk_mul_f32 v[238:239], v[92:93], v[92:93]
	v_pk_fma_f32 v[238:239], v[94:95], v[94:95], v[238:239]
	v_pk_fma_f32 v[238:239], v[88:89], v[88:89], v[238:239]
	v_pk_fma_f32 v[238:239], v[90:91], v[90:91], v[238:239]
	v_pk_fma_f32 v[238:239], v[84:85], v[84:85], v[238:239]
	v_pk_fma_f32 v[238:239], v[86:87], v[86:87], v[238:239]
	v_pk_fma_f32 v[238:239], v[80:81], v[80:81], v[238:239]
	v_pk_fma_f32 v[238:239], v[82:83], v[82:83], v[238:239]
	v_add_f32_e32 v165, v238, v239
	v_pk_mul_f32 v[240:241], v[76:77], v[76:77]
	v_pk_fma_f32 v[240:241], v[78:79], v[78:79], v[240:241]
	v_pk_fma_f32 v[240:241], v[72:73], v[72:73], v[240:241]
	v_pk_fma_f32 v[240:241], v[74:75], v[74:75], v[240:241]
	v_pk_fma_f32 v[240:241], v[68:69], v[68:69], v[240:241]
	v_pk_fma_f32 v[240:241], v[70:71], v[70:71], v[240:241]
	v_pk_fma_f32 v[240:241], v[64:65], v[64:65], v[240:241]
	v_pk_fma_f32 v[240:241], v[66:67], v[66:67], v[240:241]
	v_add_f32_e32 v171, v240, v241
	v_pk_mul_f32 v[238:239], v[60:61], v[60:61]
	v_pk_fma_f32 v[238:239], v[62:63], v[62:63], v[238:239]
	v_pk_fma_f32 v[238:239], v[56:57], v[56:57], v[238:239]
	v_pk_fma_f32 v[238:239], v[58:59], v[58:59], v[238:239]
	v_pk_fma_f32 v[238:239], v[52:53], v[52:53], v[238:239]
	v_pk_fma_f32 v[238:239], v[54:55], v[54:55], v[238:239]
	v_pk_fma_f32 v[238:239], v[48:49], v[48:49], v[238:239]
	v_pk_fma_f32 v[238:239], v[50:51], v[50:51], v[238:239]
	v_add_f32_e32 v193, v238, v239
	v_pk_mul_f32 v[240:241], v[44:45], v[44:45]
	v_pk_fma_f32 v[240:241], v[46:47], v[46:47], v[240:241]
	v_pk_fma_f32 v[240:241], v[40:41], v[40:41], v[240:241]
	v_pk_fma_f32 v[240:241], v[42:43], v[42:43], v[240:241]
	v_pk_fma_f32 v[240:241], v[36:37], v[36:37], v[240:241]
	v_pk_fma_f32 v[240:241], v[38:39], v[38:39], v[240:241]
	v_pk_fma_f32 v[240:241], v[32:33], v[32:33], v[240:241]
	v_pk_fma_f32 v[240:241], v[34:35], v[34:35], v[240:241]
	v_add_f32_e32 v233, v240, v241
	v_pk_mul_f32 v[238:239], v[28:29], v[28:29]
	v_pk_fma_f32 v[238:239], v[30:31], v[30:31], v[238:239]
	v_pk_fma_f32 v[238:239], v[24:25], v[24:25], v[238:239]
	v_pk_fma_f32 v[238:239], v[26:27], v[26:27], v[238:239]
	v_pk_fma_f32 v[238:239], v[20:21], v[20:21], v[238:239]
	v_pk_fma_f32 v[238:239], v[22:23], v[22:23], v[238:239]
	v_pk_fma_f32 v[238:239], v[16:17], v[16:17], v[238:239]
	v_pk_fma_f32 v[238:239], v[18:19], v[18:19], v[238:239]
	v_add_f32_e32 v235, v238, v239
	v_pk_mul_f32 v[240:241], v[12:13], v[12:13]
	v_pk_fma_f32 v[240:241], v[14:15], v[14:15], v[240:241]
	v_pk_fma_f32 v[240:241], v[8:9], v[8:9], v[240:241]
	v_pk_fma_f32 v[240:241], v[10:11], v[10:11], v[240:241]
	v_pk_fma_f32 v[240:241], v[4:5], v[4:5], v[240:241]
	v_pk_fma_f32 v[240:241], v[6:7], v[6:7], v[240:241]
	v_pk_fma_f32 v[240:241], v[0:1], v[0:1], v[240:241]
	v_pk_fma_f32 v[240:241], v[2:3], v[2:3], v[240:241]
	v_add_f32_e32 v237, v240, v241
	s_nop 1
	ds_bpermute_b32 v180, v194, v145
	ds_bpermute_b32 v184, v194, v155
	ds_bpermute_b32 v188, v194, v165
	ds_bpermute_b32 v196, v194, v171
	ds_bpermute_b32 v200, v194, v193
	ds_bpermute_b32 v204, v194, v233
	ds_bpermute_b32 v208, v194, v235
	ds_bpermute_b32 v212, v194, v237
	s_waitcnt lgkmcnt(0)
	v_add_f32_e32 v145, v145, v180
	v_add_f32_e32 v155, v155, v184
	v_add_f32_e32 v165, v165, v188
	v_add_f32_e32 v171, v171, v196
	v_add_f32_e32 v193, v193, v200
	v_add_f32_e32 v233, v233, v204
	v_add_f32_e32 v235, v235, v208
	v_add_f32_e32 v237, v237, v212
	s_nop 1
	ds_bpermute_b32 v180, v242, v145
	ds_bpermute_b32 v184, v242, v155
	ds_bpermute_b32 v188, v242, v165
	ds_bpermute_b32 v196, v242, v171
	ds_bpermute_b32 v200, v242, v193
	ds_bpermute_b32 v204, v242, v233
	ds_bpermute_b32 v208, v242, v235
	ds_bpermute_b32 v212, v242, v237
	s_waitcnt lgkmcnt(0)
	v_add_f32_e32 v145, v145, v180
	v_add_f32_e32 v155, v155, v184
	v_add_f32_e32 v165, v165, v188
	v_add_f32_e32 v171, v171, v196
	v_add_f32_e32 v193, v193, v200
	v_add_f32_e32 v233, v233, v204
	v_add_f32_e32 v235, v235, v208
	v_add_f32_e32 v237, v237, v212
	global_store_dword v166, v145, s[20:21]
	v_add_u32_e32 v184, 0x400, v166
	global_store_dword v184, v155, s[20:21]
	v_add_u32_e32 v188, 0x800, v166
	global_store_dword v188, v165, s[20:21]
	v_add_u32_e32 v196, 0xc00, v166
	global_store_dword v196, v171, s[20:21]
	v_add_u32_e32 v200, 0x2000, v166
	global_store_dword v200, v193, s[20:21]
	v_add_u32_e32 v204, 0x2400, v166
	global_store_dword v204, v233, s[20:21]
	v_add_u32_e32 v208, 0x2800, v166
	global_store_dword v208, v235, s[20:21]
	v_add_u32_e32 v212, 0x2c00, v166
	global_store_dword v212, v237, s[20:21]
	s_add_u32 s62, s84, 0xffffff10
	s_addc_u32 s63, s85, -1
	s_load_dwordx2 s[64:65], s[62:63], 0xb0
	s_add_u32 s66, s28, 0x5000000
	s_addc_u32 s67, s29, 0
	s_add_u32 s78, s28, 0x4c00000
	s_addc_u32 s79, s29, 0
	global_load_dwordx4 v[216:219], v153, s[66:67]
	global_load_dwordx4 v[220:223], v153, s[66:67] offset:256
	v_add_u32_e32 v240, 0x8000, v153
	global_load_dwordx4 v[224:227], v240, s[66:67]
	global_load_dwordx4 v[228:231], v240, s[66:67] offset:256
	s_waitcnt lgkmcnt(0)
	global_load_dwordx4 v[156:159], v243, s[64:65]
	global_load_dwordx4 v[160:163], v243, s[64:65] offset:16
	global_load_dwordx4 v[172:175], v243, s[64:65] offset:512
	global_load_dwordx4 v[176:179], v243, s[64:65] offset:528
	s_waitcnt vmcnt(8)
	s_barrier
; __device__ __forceinline__ unsigned xb_add(unsigned* p, unsigned v) { return __hip_atomic_fetch_add(p, v, __ATOMIC_RELAXED, __HIP_MEMORY_SCOPE_AGENT); }
; __device__ __forceinline__ void xcd_barrier(const XcdBarrier& b) {
;     ...
;     if (threadIdx.x == 0) {
;         unsigned* bar = b.bar;
;         __builtin_amdgcn_s_waitcnt(0);
;         unsigned nloc = b.st[0], nx = b.st[1];
;         if (nloc == 0u) { xcd_barrier_complete(bar, b.x, nloc, nx); b.st[0] = nloc; b.st[1] = nx; }
;         const unsigned old = xb_add(&bar[XB_XSUB(b.x)], 1u);
;         const unsigned gen = old / nloc;
;         if (old + 1u == (gen + 1u) * nloc) {
;             __builtin_amdgcn_fence(__ATOMIC_RELEASE, "agent");
;             asm volatile("s_waitcnt vmcnt(0)" ::: "memory");
;             const unsigned og = xb_add(&bar[XB_TOP], 1u);
	v_readfirstlane_b32 s94, v195
	s_cmp_lg_u32 s94, 0
	s_cbranch_scc1 .Lfe2_bskip
	s_mov_b64 exec, 1
	s_and_b32 s94, s2, 7
	s_lshl_b32 s94, s94, 3
	s_bfe_u32 s96, s2, 0x30003
	s_or_b32 s94, s94, s96
	s_lshl_b32 s94, s94, 5
	s_add_u32 s62, s28, 0x3903600
	s_addc_u32 s63, s29, 0
	v_mov_b32_e32 v238, s94
	v_mov_b32_e32 v239, 1
	s_cmp_eq_u32 s99, 1
	s_cbranch_scc1 .Lfe2_bfast
	buffer_wbl2 sc1
	s_waitcnt vmcnt(0)

; __device__ __forceinline__ float bf_lo(unsigned w) { return __uint_as_float(w << 16); }
; __device__ __forceinline__ float bf_hi(unsigned w) { return __uint_as_float(w & 0xffff0000u); }
;     __device__ __forceinline__ void operator()(const pg8::f32x4 (&acc)[2][2][4][2], const pg8::Unit& u, int wr, int wc, int fr, int fq) const {
;     ...
;         for (int ai = 0; ai < 2; ++ai) {
;             v4u gq[4][2], aq[4][2];
;             if (GATE) {
; #pragma unroll
;                 for (int m = 0; m < 4; ++m)
; #pragma unroll
;                     for (int bj = 0; bj < 2; ++bj) gq[m][bj] = *(const v4u*)(G + (size_t)(row0 + ai * 128 + m * 16) * D + col0 + bj * 128);
;             }
;             if (ADD) {
; #pragma unroll
;                 for (int m = 0; m < 4; ++m)
; #pragma unroll
;                     for (int bj = 0; bj < 2; ++bj) aq[m][bj] = *(const v4u*)(A2 + (size_t)(row0 + ai * 128 + m * 16) * D + col0 + bj * 128);
;             }
; #pragma unroll
;             for (int m = 0; m < 4; ++m) {
;                 const int row = row0 + ai * 128 + m * 16;
;                 const size_t off = (size_t)row * D + col0;
;                 float s = 0.f;
; #pragma unroll
;                 for (int bj = 0; bj < 2; ++bj) {
;                     float r[8];
; #pragma unroll
;                     for (int j = 0; j < 4; ++j) { r[j] = acc[ai][bj][m][0][j]; r[4 + j] = acc[ai][bj][m][1][j]; }
;                     if (RSCALE) { const float rv = rvs[ai][m];
; #pragma unroll
;                         for (int j = 0; j < 8; ++j) r[j] *= rv; }
;                     if (ACT == 1) {
; #pragma unroll
;                         for (int j = 0; j < 8; ++j) r[j] = sigmoid_fast(r[j]);
;                     }
;                     if (GATE) { const v4u g = gq[m][bj];
;                         r[0] *= bf_lo(g.x); r[1] *= bf_hi(g.x); r[2] *= bf_lo(g.y); r[3] *= bf_hi(g.y); r[4] *= bf_lo(g.z); r[5] *= bf_hi(g.z); r[6] *= bf_lo(g.w); r[7] *= bf_hi(g.w); }
;                     if (ADD) { const v4u g = aq[m][bj];
;                         r[0] += bf_lo(g.x); r[1] += bf_hi(g.x); r[2] += bf_lo(g.y); r[3] += bf_hi(g.y); r[4] += bf_lo(g.z); r[5] += bf_hi(g.z); r[6] += bf_lo(g.w); r[7] += bf_hi(g.w); }
;                     if (PART) {
; #pragma unroll
;                         for (int j = 0; j < 8; ++j) s += r[j] * r[j];
.LBB0_1392:
	s_waitcnt lgkmcnt(0)
	v_lshl_or_b32 v128, s58, 8, v172
	v_lshl_add_u32 v154, s57, 8, v170
	v_lshlrev_b32_e32 v156, 2, v128
	v_lshlrev_b32_e32 v129, 1, v128
	v_lshl_add_u32 v152, v154, 11, v129
	v_xor_b32_e32 v130, 16, v176
	v_lshlrev_b32_e32 v177, 2, v130
	v_xor_b32_e32 v130, 32, v176
	v_lshlrev_b32_e32 v155, 2, v130
	v_lshrrev_b32_e32 v130, 4, v176
	v_and_b32_e32 v130, 3, v130
	v_lshlrev_b32_e32 v157, 4, v130
	s_lshl_b32 s38, s58, 4
	s_add_u32 s38, s38, s14
	v_lshl_add_u32 v153, v154, 6, s38
	global_load_dwordx4 v[178:181], v152, s[16:17]
	global_load_dwordx4 v[182:185], v152, s[16:17] offset:256
	v_add_u32_e32 v159, 0x8000, v152
	global_load_dwordx4 v[186:189], v159, s[16:17]
	global_load_dwordx4 v[190:193], v159, s[16:17] offset:256
	v_add_u32_e32 v160, 0x10000, v152
	global_load_dwordx4 v[196:199], v160, s[16:17]
	global_load_dwordx4 v[200:203], v160, s[16:17] offset:256
	v_add_u32_e32 v161, 0x18000, v152
	global_load_dwordx4 v[204:207], v161, s[16:17]
	global_load_dwordx4 v[208:211], v161, s[16:17] offset:256
	v_add_u32_e32 v162, 0x40000, v152
	global_load_dwordx4 v[212:215], v162, s[16:17]
	global_load_dwordx4 v[216:219], v162, s[16:17] offset:256
	v_add_u32_e32 v163, 0x48000, v152
	global_load_dwordx4 v[220:223], v163, s[16:17]
	global_load_dwordx4 v[224:227], v163, s[16:17] offset:256
	v_add_u32_e32 v164, 0x50000, v152
	global_load_dwordx4 v[228:231], v164, s[16:17]
	global_load_dwordx4 v[232:235], v164, s[16:17] offset:256
	v_add_u32_e32 v165, 0x58000, v152
	global_load_dwordx4 v[236:239], v165, s[16:17]
	global_load_dwordx4 v[240:243], v165, s[16:17] offset:256
	s_waitcnt vmcnt(14)
	v_lshlrev_b32_e32 v248, 16, v178
	v_and_b32_e32 v249, 0xffff0000, v178
	v_pk_mul_f32 v[124:125], v[124:125], v[248:249]
	v_lshlrev_b32_e32 v250, 16, v179
	v_and_b32_e32 v251, 0xffff0000, v179
	v_pk_mul_f32 v[126:127], v[126:127], v[250:251]
	v_lshlrev_b32_e32 v252, 16, v180
	v_and_b32_e32 v253, 0xffff0000, v180
	v_pk_mul_f32 v[120:121], v[120:121], v[252:253]
	v_lshlrev_b32_e32 v248, 16, v181
	v_and_b32_e32 v249, 0xffff0000, v181
	v_pk_mul_f32 v[122:123], v[122:123], v[248:249]
	v_lshlrev_b32_e32 v250, 16, v182
	v_and_b32_e32 v251, 0xffff0000, v182
	v_pk_mul_f32 v[116:117], v[116:117], v[250:251]
	v_lshlrev_b32_e32 v252, 16, v183
	v_and_b32_e32 v253, 0xffff0000, v183
	v_pk_mul_f32 v[118:119], v[118:119], v[252:253]
	v_lshlrev_b32_e32 v248, 16, v184
	v_and_b32_e32 v249, 0xffff0000, v184
	v_pk_mul_f32 v[112:113], v[112:113], v[248:249]
	v_lshlrev_b32_e32 v250, 16, v185
	v_and_b32_e32 v251, 0xffff0000, v185
	v_pk_mul_f32 v[114:115], v[114:115], v[250:251]
	v_pk_mul_f32 v[244:245], v[124:125], v[124:125]
	v_pk_fma_f32 v[244:245], v[126:127], v[126:127], v[244:245]
	v_pk_fma_f32 v[244:245], v[120:121], v[120:121], v[244:245]
	v_pk_fma_f32 v[244:245], v[122:123], v[122:123], v[244:245]
	v_pk_fma_f32 v[244:245], v[116:117], v[116:117], v[244:245]
	v_pk_fma_f32 v[244:245], v[118:119], v[118:119], v[244:245]
	v_pk_fma_f32 v[244:245], v[112:113], v[112:113], v[244:245]
	v_pk_fma_f32 v[244:245], v[114:115], v[114:115], v[244:245]
	v_add_f32_e32 v128, v244, v245
	s_waitcnt vmcnt(12)
	v_lshlrev_b32_e32 v248, 16, v186
	v_and_b32_e32 v249, 0xffff0000, v186
	v_pk_mul_f32 v[108:109], v[108:109], v[248:249]
	v_lshlrev_b32_e32 v250, 16, v187
	v_and_b32_e32 v251, 0xffff0000, v187
	v_pk_mul_f32 v[110:111], v[110:111], v[250:251]
	v_lshlrev_b32_e32 v252, 16, v188
	v_and_b32_e32 v253, 0xffff0000, v188
	v_pk_mul_f32 v[104:105], v[104:105], v[252:253]
	v_lshlrev_b32_e32 v248, 16, v189
	v_and_b32_e32 v249, 0xffff0000, v189
	v_pk_mul_f32 v[106:107], v[106:107], v[248:249]
	v_lshlrev_b32_e32 v250, 16, v190
	v_and_b32_e32 v251, 0xffff0000, v190
	v_pk_mul_f32 v[100:101], v[100:101], v[250:251]
	v_lshlrev_b32_e32 v252, 16, v191
	v_and_b32_e32 v253, 0xffff0000, v191
	v_pk_mul_f32 v[102:103], v[102:103], v[252:253]
	v_lshlrev_b32_e32 v248, 16, v192
	v_and_b32_e32 v249, 0xffff0000, v192
	v_pk_mul_f32 v[96:97], v[96:97], v[248:249]
	v_lshlrev_b32_e32 v250, 16, v193
	v_and_b32_e32 v251, 0xffff0000, v193
	v_pk_mul_f32 v[98:99], v[98:99], v[250:251]
	v_pk_mul_f32 v[244:245], v[108:109], v[108:109]
	v_pk_fma_f32 v[244:245], v[110:111], v[110:111], v[244:245]
	v_pk_fma_f32 v[244:245], v[104:105], v[104:105], v[244:245]
	v_pk_fma_f32 v[244:245], v[106:107], v[106:107], v[244:245]
	v_pk_fma_f32 v[244:245], v[100:101], v[100:101], v[244:245]
	v_pk_fma_f32 v[244:245], v[102:103], v[102:103], v[244:245]
	v_pk_fma_f32 v[244:245], v[96:97], v[96:97], v[244:245]
	v_pk_fma_f32 v[244:245], v[98:99], v[98:99], v[244:245]
	v_add_f32_e32 v129, v244, v245
	s_waitcnt vmcnt(10)
	v_lshlrev_b32_e32 v248, 16, v196
	v_and_b32_e32 v249, 0xffff0000, v196
	v_pk_mul_f32 v[92:93], v[92:93], v[248:249]
	v_lshlrev_b32_e32 v250, 16, v197
	v_and_b32_e32 v251, 0xffff0000, v197
	v_pk_mul_f32 v[94:95], v[94:95], v[250:251]
	v_lshlrev_b32_e32 v252, 16, v198
	v_and_b32_e32 v253, 0xffff0000, v198
	v_pk_mul_f32 v[88:89], v[88:89], v[252:253]
	v_lshlrev_b32_e32 v248, 16, v199
	v_and_b32_e32 v249, 0xffff0000, v199
	v_pk_mul_f32 v[90:91], v[90:91], v[248:249]
	v_lshlrev_b32_e32 v250, 16, v200
	v_and_b32_e32 v251, 0xffff0000, v200
	v_pk_mul_f32 v[84:85], v[84:85], v[250:251]
	v_lshlrev_b32_e32 v252, 16, v201
	v_and_b32_e32 v253, 0xffff0000, v201
	v_pk_mul_f32 v[86:87], v[86:87], v[252:253]
	v_lshlrev_b32_e32 v248, 16, v202
	v_and_b32_e32 v249, 0xffff0000, v202
	v_pk_mul_f32 v[80:81], v[80:81], v[248:249]
	v_lshlrev_b32_e32 v250, 16, v203
	v_and_b32_e32 v251, 0xffff0000, v203
	v_pk_mul_f32 v[82:83], v[82:83], v[250:251]
	v_pk_mul_f32 v[244:245], v[92:93], v[92:93]
	v_pk_fma_f32 v[244:245], v[94:95], v[94:95], v[244:245]
	v_pk_fma_f32 v[244:245], v[88:89], v[88:89], v[244:245]
	v_pk_fma_f32 v[244:245], v[90:91], v[90:91], v[244:245]
	v_pk_fma_f32 v[244:245], v[84:85], v[84:85], v[244:245]
	v_pk_fma_f32 v[244:245], v[86:87], v[86:87], v[244:245]
	v_pk_fma_f32 v[244:245], v[80:81], v[80:81], v[244:245]
	v_pk_fma_f32 v[244:245], v[82:83], v[82:83], v[244:245]
	v_add_f32_e32 v130, v244, v245
	s_waitcnt vmcnt(8)
; __device__ __forceinline__ float bf_lo(unsigned w) { return __uint_as_float(w << 16); }
; __device__ __forceinline__ float bf_hi(unsigned w) { return __uint_as_float(w & 0xffff0000u); }
; __device__ __forceinline__ float sigmoid_fast(float x) { return __builtin_amdgcn_rcpf(1.0f + __builtin_amdgcn_exp2f(-1.44269504089f * x)); }
;     __device__ __forceinline__ void operator()(const pg8::f32x4 (&acc)[2][2][4][2], const pg8::Unit& u, int wr, int wc, int fr, int fq) const {
;     ...
;             for (int m = 0; m < 4; ++m) {
;                 const int row = row0 + ai * 128 + m * 16;
;                 const size_t off = (size_t)row * D + col0;
;                 float s = 0.f;
; #pragma unroll
;                 for (int bj = 0; bj < 2; ++bj) {
;                     float r[8];
; #pragma unroll
;                     for (int j = 0; j < 4; ++j) { r[j] = acc[ai][bj][m][0][j]; r[4 + j] = acc[ai][bj][m][1][j]; }
;                     if (RSCALE) { const float rv = rvs[ai][m];
; #pragma unroll
;                         for (int j = 0; j < 8; ++j) r[j] *= rv; }
;                     if (ACT == 1) {
; #pragma unroll
;                         for (int j = 0; j < 8; ++j) r[j] = sigmoid_fast(r[j]);
;                     }
;                     if (GATE) { const v4u g = gq[m][bj];
;                         r[0] *= bf_lo(g.x); r[1] *= bf_hi(g.x); r[2] *= bf_lo(g.y); r[3] *= bf_hi(g.y); r[4] *= bf_lo(g.z); r[5] *= bf_hi(g.z); r[6] *= bf_lo(g.w); r[7] *= bf_hi(g.w); }
;                     if (ADD) { const v4u g = aq[m][bj];
;                         r[0] += bf_lo(g.x); r[1] += bf_hi(g.x); r[2] += bf_lo(g.y); r[3] += bf_hi(g.y); r[4] += bf_lo(g.z); r[5] += bf_hi(g.z); r[6] += bf_lo(g.w); r[7] += bf_hi(g.w); }
;                     if (PART) {
; #pragma unroll
;                         for (int j = 0; j < 8; ++j) s += r[j] * r[j];
	v_lshlrev_b32_e32 v248, 16, v204
	v_and_b32_e32 v249, 0xffff0000, v204
	v_pk_mul_f32 v[76:77], v[76:77], v[248:249]
	v_lshlrev_b32_e32 v250, 16, v205
	v_and_b32_e32 v251, 0xffff0000, v205
	v_pk_mul_f32 v[78:79], v[78:79], v[250:251]
	v_lshlrev_b32_e32 v252, 16, v206
	v_and_b32_e32 v253, 0xffff0000, v206
	v_pk_mul_f32 v[72:73], v[72:73], v[252:253]
	v_lshlrev_b32_e32 v248, 16, v207
	v_and_b32_e32 v249, 0xffff0000, v207
	v_pk_mul_f32 v[74:75], v[74:75], v[248:249]
	v_lshlrev_b32_e32 v250, 16, v208
	v_and_b32_e32 v251, 0xffff0000, v208
	v_pk_mul_f32 v[68:69], v[68:69], v[250:251]
	v_lshlrev_b32_e32 v252, 16, v209
	v_and_b32_e32 v253, 0xffff0000, v209
	v_pk_mul_f32 v[70:71], v[70:71], v[252:253]
	v_lshlrev_b32_e32 v248, 16, v210
	v_and_b32_e32 v249, 0xffff0000, v210
	v_pk_mul_f32 v[64:65], v[64:65], v[248:249]
	v_lshlrev_b32_e32 v250, 16, v211
	v_and_b32_e32 v251, 0xffff0000, v211
	v_pk_mul_f32 v[66:67], v[66:67], v[250:251]
	v_pk_mul_f32 v[244:245], v[76:77], v[76:77]
	v_pk_fma_f32 v[244:245], v[78:79], v[78:79], v[244:245]
	v_pk_fma_f32 v[244:245], v[72:73], v[72:73], v[244:245]
	v_pk_fma_f32 v[244:245], v[74:75], v[74:75], v[244:245]
	v_pk_fma_f32 v[244:245], v[68:69], v[68:69], v[244:245]
	v_pk_fma_f32 v[244:245], v[70:71], v[70:71], v[244:245]
	v_pk_fma_f32 v[244:245], v[64:65], v[64:65], v[244:245]
	v_pk_fma_f32 v[244:245], v[66:67], v[66:67], v[244:245]
	v_add_f32_e32 v131, v244, v245
	s_waitcnt vmcnt(6)
	v_lshlrev_b32_e32 v248, 16, v212
	v_and_b32_e32 v249, 0xffff0000, v212
	v_pk_mul_f32 v[60:61], v[60:61], v[248:249]
	v_lshlrev_b32_e32 v250, 16, v213
	v_and_b32_e32 v251, 0xffff0000, v213
	v_pk_mul_f32 v[62:63], v[62:63], v[250:251]
	v_lshlrev_b32_e32 v252, 16, v214
	v_and_b32_e32 v253, 0xffff0000, v214
	v_pk_mul_f32 v[56:57], v[56:57], v[252:253]
	v_lshlrev_b32_e32 v248, 16, v215
	v_and_b32_e32 v249, 0xffff0000, v215
	v_pk_mul_f32 v[58:59], v[58:59], v[248:249]
	v_lshlrev_b32_e32 v250, 16, v216
	v_and_b32_e32 v251, 0xffff0000, v216
	v_pk_mul_f32 v[52:53], v[52:53], v[250:251]
	v_lshlrev_b32_e32 v252, 16, v217
	v_and_b32_e32 v253, 0xffff0000, v217
	v_pk_mul_f32 v[54:55], v[54:55], v[252:253]
	v_lshlrev_b32_e32 v248, 16, v218
	v_and_b32_e32 v249, 0xffff0000, v218
	v_pk_mul_f32 v[48:49], v[48:49], v[248:249]
	v_lshlrev_b32_e32 v250, 16, v219
	v_and_b32_e32 v251, 0xffff0000, v219
	v_pk_mul_f32 v[50:51], v[50:51], v[250:251]
	v_pk_mul_f32 v[244:245], v[60:61], v[60:61]
	v_pk_fma_f32 v[244:245], v[62:63], v[62:63], v[244:245]
	v_pk_fma_f32 v[244:245], v[56:57], v[56:57], v[244:245]
	v_pk_fma_f32 v[244:245], v[58:59], v[58:59], v[244:245]
	v_pk_fma_f32 v[244:245], v[52:53], v[52:53], v[244:245]
	v_pk_fma_f32 v[244:245], v[54:55], v[54:55], v[244:245]
	v_pk_fma_f32 v[244:245], v[48:49], v[48:49], v[244:245]
	v_pk_fma_f32 v[244:245], v[50:51], v[50:51], v[244:245]
	v_add_f32_e32 v132, v244, v245
	s_waitcnt vmcnt(4)
	v_lshlrev_b32_e32 v248, 16, v220
	v_and_b32_e32 v249, 0xffff0000, v220
	v_pk_mul_f32 v[44:45], v[44:45], v[248:249]
	v_lshlrev_b32_e32 v250, 16, v221
	v_and_b32_e32 v251, 0xffff0000, v221
	v_pk_mul_f32 v[46:47], v[46:47], v[250:251]
	v_lshlrev_b32_e32 v252, 16, v222
	v_and_b32_e32 v253, 0xffff0000, v222
	v_pk_mul_f32 v[40:41], v[40:41], v[252:253]
	v_lshlrev_b32_e32 v248, 16, v223
	v_and_b32_e32 v249, 0xffff0000, v223
	v_pk_mul_f32 v[42:43], v[42:43], v[248:249]
	v_lshlrev_b32_e32 v250, 16, v224
	v_and_b32_e32 v251, 0xffff0000, v224
	v_pk_mul_f32 v[36:37], v[36:37], v[250:251]
	v_lshlrev_b32_e32 v252, 16, v225
	v_and_b32_e32 v253, 0xffff0000, v225
	v_pk_mul_f32 v[38:39], v[38:39], v[252:253]
	v_lshlrev_b32_e32 v248, 16, v226
	v_and_b32_e32 v249, 0xffff0000, v226
	v_pk_mul_f32 v[32:33], v[32:33], v[248:249]
	v_lshlrev_b32_e32 v250, 16, v227
	v_and_b32_e32 v251, 0xffff0000, v227
	v_pk_mul_f32 v[34:35], v[34:35], v[250:251]
	v_pk_mul_f32 v[244:245], v[44:45], v[44:45]
	v_pk_fma_f32 v[244:245], v[46:47], v[46:47], v[244:245]
	v_pk_fma_f32 v[244:245], v[40:41], v[40:41], v[244:245]
	v_pk_fma_f32 v[244:245], v[42:43], v[42:43], v[244:245]
	v_pk_fma_f32 v[244:245], v[36:37], v[36:37], v[244:245]
	v_pk_fma_f32 v[244:245], v[38:39], v[38:39], v[244:245]
	v_pk_fma_f32 v[244:245], v[32:33], v[32:33], v[244:245]
	v_pk_fma_f32 v[244:245], v[34:35], v[34:35], v[244:245]
	v_add_f32_e32 v133, v244, v245
	s_waitcnt vmcnt(2)
;     __device__ __forceinline__ void operator()(const pg8::f32x4 (&acc)[2][2][4][2], const pg8::Unit& u, int wr, int wc, int fr, int fq) const {
;     ...
;             for (int m = 0; m < 4; ++m) {
;                 const int row = row0 + ai * 128 + m * 16;
;                 const size_t off = (size_t)row * D + col0;
;                 float s = 0.f;
; #pragma unroll
;                 for (int bj = 0; bj < 2; ++bj) {
;                     float r[8];
; #pragma unroll
;                     for (int j = 0; j < 4; ++j) { r[j] = acc[ai][bj][m][0][j]; r[4 + j] = acc[ai][bj][m][1][j]; }
;                     if (RSCALE) { const float rv = rvs[ai][m];
; #pragma unroll
;                         for (int j = 0; j < 8; ++j) r[j] *= rv; }
;                     if (ACT == 1) {
; #pragma unroll
;                         for (int j = 0; j < 8; ++j) r[j] = sigmoid_fast(r[j]);
;                     }
;                     if (GATE) { const v4u g = gq[m][bj];
;                         r[0] *= bf_lo(g.x); r[1] *= bf_hi(g.x); r[2] *= bf_lo(g.y); r[3] *= bf_hi(g.y); r[4] *= bf_lo(g.z); r[5] *= bf_hi(g.z); r[6] *= bf_lo(g.w); r[7] *= bf_hi(g.w); }
;                     if (ADD) { const v4u g = aq[m][bj];
;                         r[0] += bf_lo(g.x); r[1] += bf_hi(g.x); r[2] += bf_lo(g.y); r[3] += bf_hi(g.y); r[4] += bf_lo(g.z); r[5] += bf_hi(g.z); r[6] += bf_lo(g.w); r[7] += bf_hi(g.w); }
;                     if (PART) {
; #pragma unroll
;                         for (int j = 0; j < 8; ++j) s += r[j] * r[j];
;                     }
;                     v4u w; w.x = pk2(r[0], r[1]); w.y = pk2(r[2], r[3]); w.z = pk2(r[4], r[5]); w.w = pk2(r[6], r[7]);
;                     st16_wt(O + off + bj * 128, w);
;                 }
;                 if (PART) { s += __shfl_xor(s, 16); s += __shfl_xor(s, 32); st4_wt(part + (size_t)row * 16 + u.pn * 4 + wc, s); }
; template <bool SRC_F32, int R> __device__ __forceinline__ void ew_load(EwSet<SRC_F32, R>& S, int rb, const float* hsrc32, const bf16* hsrcb, const bf16* f, const float* part, int lane) {
; #pragma unroll
;     for (int i = 0; i < R; ++i) S.p[i] = (lane < 16) ? part[(size_t)(rb + i) * 16 + lane] : 0.f;
; #pragma unroll
;     for (int i = 0; i < R; ++i)
; #pragma unroll
;         for (int j = 0; j < 4; ++j) {
;             S.fw[i][j] = ((const v2u*)(f + (size_t)(rb + i) * D) + lane)[64 * j];
	v_lshlrev_b32_e32 v248, 16, v228
	v_and_b32_e32 v249, 0xffff0000, v228
	v_pk_mul_f32 v[28:29], v[28:29], v[248:249]
	v_lshlrev_b32_e32 v250, 16, v229
	v_and_b32_e32 v251, 0xffff0000, v229
	v_pk_mul_f32 v[30:31], v[30:31], v[250:251]
	v_lshlrev_b32_e32 v252, 16, v230
	v_and_b32_e32 v253, 0xffff0000, v230
	v_pk_mul_f32 v[24:25], v[24:25], v[252:253]
	v_lshlrev_b32_e32 v248, 16, v231
	v_and_b32_e32 v249, 0xffff0000, v231
	v_pk_mul_f32 v[26:27], v[26:27], v[248:249]
	v_lshlrev_b32_e32 v250, 16, v232
	v_and_b32_e32 v251, 0xffff0000, v232
	v_pk_mul_f32 v[20:21], v[20:21], v[250:251]
	v_lshlrev_b32_e32 v252, 16, v233
	v_and_b32_e32 v253, 0xffff0000, v233
	v_pk_mul_f32 v[22:23], v[22:23], v[252:253]
	v_lshlrev_b32_e32 v248, 16, v234
	v_and_b32_e32 v249, 0xffff0000, v234
	v_pk_mul_f32 v[16:17], v[16:17], v[248:249]
	v_lshlrev_b32_e32 v250, 16, v235
	v_and_b32_e32 v251, 0xffff0000, v235
	v_pk_mul_f32 v[18:19], v[18:19], v[250:251]
	v_pk_mul_f32 v[244:245], v[28:29], v[28:29]
	v_pk_fma_f32 v[244:245], v[30:31], v[30:31], v[244:245]
	v_pk_fma_f32 v[244:245], v[24:25], v[24:25], v[244:245]
	v_pk_fma_f32 v[244:245], v[26:27], v[26:27], v[244:245]
	v_pk_fma_f32 v[244:245], v[20:21], v[20:21], v[244:245]
	v_pk_fma_f32 v[244:245], v[22:23], v[22:23], v[244:245]
	v_pk_fma_f32 v[244:245], v[16:17], v[16:17], v[244:245]
	v_pk_fma_f32 v[244:245], v[18:19], v[18:19], v[244:245]
	v_add_f32_e32 v134, v244, v245
	s_waitcnt vmcnt(0)
	v_lshlrev_b32_e32 v248, 16, v236
	v_and_b32_e32 v249, 0xffff0000, v236
	v_pk_mul_f32 v[12:13], v[12:13], v[248:249]
	v_lshlrev_b32_e32 v250, 16, v237
	v_and_b32_e32 v251, 0xffff0000, v237
	v_pk_mul_f32 v[14:15], v[14:15], v[250:251]
	v_lshlrev_b32_e32 v252, 16, v238
	v_and_b32_e32 v253, 0xffff0000, v238
	v_pk_mul_f32 v[8:9], v[8:9], v[252:253]
	v_lshlrev_b32_e32 v248, 16, v239
	v_and_b32_e32 v249, 0xffff0000, v239
	v_pk_mul_f32 v[10:11], v[10:11], v[248:249]
	v_lshlrev_b32_e32 v250, 16, v240
	v_and_b32_e32 v251, 0xffff0000, v240
	v_pk_mul_f32 v[4:5], v[4:5], v[250:251]
	v_lshlrev_b32_e32 v252, 16, v241
	v_and_b32_e32 v253, 0xffff0000, v241
	v_pk_mul_f32 v[6:7], v[6:7], v[252:253]
	v_lshlrev_b32_e32 v248, 16, v242
	v_and_b32_e32 v249, 0xffff0000, v242
	v_pk_mul_f32 v[0:1], v[0:1], v[248:249]
	v_lshlrev_b32_e32 v250, 16, v243
	v_and_b32_e32 v251, 0xffff0000, v243
	v_pk_mul_f32 v[2:3], v[2:3], v[250:251]
	v_pk_mul_f32 v[244:245], v[12:13], v[12:13]
	v_pk_fma_f32 v[244:245], v[14:15], v[14:15], v[244:245]
	v_pk_fma_f32 v[244:245], v[8:9], v[8:9], v[244:245]
	v_pk_fma_f32 v[244:245], v[10:11], v[10:11], v[244:245]
	v_pk_fma_f32 v[244:245], v[4:5], v[4:5], v[244:245]
	v_pk_fma_f32 v[244:245], v[6:7], v[6:7], v[244:245]
	v_pk_fma_f32 v[244:245], v[0:1], v[0:1], v[244:245]
	v_pk_fma_f32 v[244:245], v[2:3], v[2:3], v[244:245]
	v_add_f32_e32 v135, v244, v245
	s_nop 1
	ds_bpermute_b32 v158, v177, v128
	ds_bpermute_b32 v159, v177, v129
	ds_bpermute_b32 v160, v177, v130
	ds_bpermute_b32 v161, v177, v131
	ds_bpermute_b32 v162, v177, v132
	ds_bpermute_b32 v163, v177, v133
	ds_bpermute_b32 v164, v177, v134
	ds_bpermute_b32 v165, v177, v135
	s_waitcnt lgkmcnt(0)
	v_add_f32_e32 v128, v128, v158
	v_add_f32_e32 v129, v129, v159
	v_add_f32_e32 v130, v130, v160
	v_add_f32_e32 v131, v131, v161
	v_add_f32_e32 v132, v132, v162
	v_add_f32_e32 v133, v133, v163
	v_add_f32_e32 v134, v134, v164
	v_add_f32_e32 v135, v135, v165
	s_nop 1
	ds_bpermute_b32 v158, v155, v128
	ds_bpermute_b32 v159, v155, v129
	ds_bpermute_b32 v160, v155, v130
	ds_bpermute_b32 v161, v155, v131
	ds_bpermute_b32 v162, v155, v132
	ds_bpermute_b32 v163, v155, v133
	ds_bpermute_b32 v164, v155, v134
	ds_bpermute_b32 v165, v155, v135
	s_waitcnt lgkmcnt(0)
	v_add_f32_e32 v128, v128, v158
	v_add_f32_e32 v129, v129, v159
	v_add_f32_e32 v130, v130, v160
	v_add_f32_e32 v131, v131, v161
	v_add_f32_e32 v132, v132, v162
	v_add_f32_e32 v133, v133, v163
	v_add_f32_e32 v134, v134, v164
	v_add_f32_e32 v135, v135, v165
	global_store_dword v153, v128, s[20:21]
	v_add_u32_e32 v159, 0x400, v153
	global_store_dword v159, v129, s[20:21]
	v_add_u32_e32 v160, 0x800, v153
	global_store_dword v160, v130, s[20:21]
	v_add_u32_e32 v161, 0xc00, v153
	global_store_dword v161, v131, s[20:21]
	v_add_u32_e32 v162, 0x2000, v153
	global_store_dword v162, v132, s[20:21]
	v_add_u32_e32 v163, 0x2400, v153
	global_store_dword v163, v133, s[20:21]
	v_add_u32_e32 v164, 0x2800, v153
	global_store_dword v164, v134, s[20:21]
	v_add_u32_e32 v165, 0x2c00, v153
	global_store_dword v165, v135, s[20:21]
	s_add_u32 s60, s84, 0xffffff10
	s_addc_u32 s61, s85, -1
	s_load_dwordx2 s[62:63], s[60:61], 0xd0
	s_load_dwordx2 s[64:65], s[60:61], 0xd8
	s_add_u32 s66, s28, 0x5000000
	s_addc_u32 s67, s29, 0
	global_load_dwordx4 v[178:181], v152, s[66:67]
	global_load_dwordx4 v[182:185], v152, s[66:67] offset:256
	v_add_u32_e32 v159, 0x8000, v152
	global_load_dwordx4 v[186:189], v159, s[66:67]
	global_load_dwordx4 v[190:193], v159, s[66:67] offset:256
	s_waitcnt lgkmcnt(0)
	global_load_dwordx4 v[228:231], v156, s[62:63]
	global_load_dwordx4 v[232:235], v156, s[62:63] offset:16
	global_load_dwordx4 v[236:239], v156, s[62:63] offset:512
	global_load_dwordx4 v[240:243], v156, s[62:63] offset:528
	s_waitcnt vmcnt(8)
	s_barrier
	v_readfirstlane_b32 s59, v195
	s_cmp_lg_u32 s59, 0
	s_cbranch_scc1 .Lp13_bskip
	s_mov_b64 exec, 1
	s_and_b32 s59, s2, 7
	s_lshl_b32 s59, s59, 3
	s_bfe_u32 s60, s2, 0x30003
	s_or_b32 s59, s59, s60
	s_lshl_b32 s59, s59, 5
	s_add_u32 s60, s28, 0x3903600
	s_addc_u32 s61, s29, 0
	v_mov_b32_e32 v244, s59
	v_mov_b32_e32 v245, 1
	s_cmp_eq_u32 s99, 1
	s_cbranch_scc1 .Lp13_bfast
	buffer_wbl2 sc1
	s_waitcnt vmcnt(0)
